# mLSTM chunk loop: static s_setprio 1 for waves 0-3 (S^T critical path)
# speedup vs baseline: 1.0082x; 1.0082x over previous
; __global__ void __launch_bounds__(512, 2) fwd_megakernel(Args a) {
;     ...
;         for (int it = bid; it < 256; it += G) { const int x = it & 7, loc = it >> 3, bh = x * 8 + (loc >> 2); mlstm_item(a, L, false, bh >> 2, bh & 3, loc & 3); }
.LBB0_644:
	s_or_b64 exec, exec, s[0:1]
	s_setprio 0
	s_waitcnt lgkmcnt(0)
	s_barrier
	s_add_i32 s92, s92, s30
	s_add_i32 s91, s91, s34
	s_cmpk_gt_i32 s92, 0xff
	s_cbranch_scc1 .LBB0_707

; #define LAS __attribute__((address_space(3)))
; __device__ __forceinline__ float bf2f(unsigned b) { return __uint_as_float(b << 16); }
; __device__ __forceinline__ unsigned pk2(float lo, float hi) { unsigned r; asm("v_cvt_pk_bf16_f32 %0, %1, %2" : "=v"(r) : "v"(lo), "v"(hi)); return r; }
; #define LDS_BARRIER() do { asm volatile("s_waitcnt lgkmcnt(0)" ::: "memory"); __builtin_amdgcn_s_barrier(); asm volatile("" ::: "memory"); } while (0)
; __device__ __forceinline__ void mlstm_item(const Args& a, LAS unsigned char* L, bool sample, int b, int hh, int sl, bool dry = false) {
;     ...
;     for (int c = 0; c < nchunks; ++c) {
; #pragma unroll
;         for (int i = 0; i < 2; ++i) { *(LAS u32x4*)(L + L_QS + (prow + 16 * i) * 528 + pcc * 16) = qreg[i]; *(LAS u32x4*)(L + L_KS + (prow + 16 * i) * 528 + pcc * 16) = kreg[i]; }
;         if (tid < 256) {
;             const float wL0 = GWL[c * 32 + 2 * sp], wL1 = GWL[c * 32 + 2 * sp + 1];
;             const unsigned r0w[2] = {vreg0.x, vreg0.y}, r1w[2] = {vreg1.x, vreg1.y};
; #pragma unroll
;             for (int i = 0; i < 4; ++i) { const unsigned e0 = (i & 1) ? (r0w[i >> 1] >> 16) : (r0w[i >> 1] & 0xffffu), e1 = (i & 1) ? (r1w[i >> 1] >> 16) : (r1w[i >> 1] & 0xffffu);
;                 *(LAS unsigned*)(L + L_VT + (vq * 4 + i) * 80 + sp * 4) = e0 | (e1 << 16);
;                 *(LAS unsigned*)(L + L_VTW + (vq * 4 + i) * 80 + sp * 4) = pk2(bf2f(e0) * wL0, bf2f(e1) * wL1); }
;             if (tid < 16) *(LAS unsigned*)(L + L_VTW + 64 * 80 + sp * 4) = pk2(wL0, wL1);
;         }
;         if (c + 1 < nchunks) PREFETCH(c + 1);
;         LDS_BARRIER();
;         const float dL = GDL[c], m0c = GM0[c];
;         if (wave < 4) {
.LBB0_659:
	s_or_b64 exec, exec, s[4:5]
	s_lshr_b32 s4, s92, 3
	s_and_b32 s59, s4, 3
	s_lshl_b32 s97, s94, 6
	s_cmp_gt_i32 s55, 3
	s_cselect_b64 s[68:69], -1, 0
	s_add_i32 s4, s55, -4
	s_lshr_b32 s6, s4, 1
	v_and_b32_e32 v99, 48, v83
	v_bfe_u32 v222, v83, 5, 1
	v_lshlrev_b32_e32 v222, 4, v222
	v_bfe_u32 v223, v83, 4, 1
	v_lshl_or_b32 v222, v223, 8, v222
	v_bfe_u32 v223, v83, 5, 1
	v_mul_u32_u24_e32 v223, 0xf0, v223
	v_lshrrev_b32_e32 v226, 1, v83
	v_and_b32_e32 v226, 0xffffffe0, v226
	v_sub_u32_e32 v223, v223, v226
	v_bfe_u32 v224, v83, 2, 3
	v_lshlrev_b32_e32 v224, 5, v224
	v_bfe_u32 v227, v83, 1, 1
	v_lshl_or_b32 v224, v227, 4, v224
	v_and_b32_e32 v228, 1, v83
	v_lshl_or_b32 v224, v228, 8, v224
	v_lshlrev_b32_e32 v225, 8, v227
	v_lshl_or_b32 v225, v228, 3, v225
	v_add_u32_e32 v225, v225, v226
	s_lshl_b32 s4, s55, 4
	v_lshl_add_u32 v103, s6, 7, v222
	s_lshl_b32 s6, s6, 5
	v_lshlrev_b32_e32 v66, 2, v84
	s_and_b32 s17, s4, 16
	s_add_i32 s6, s6, 64
	s_ashr_i32 s70, s12, 7
	s_bfe_u32 s71, s12, 0x10006
	v_lshl_add_u32 v21, v24, 4, 0
	v_add_u32_e32 v106, 0, v66
	v_or_b32_e32 v88, s17, v84
	v_mul_u32_u24_e32 v24, 0x20c, v84
	s_mov_b32 s4, 0xc000
	s_cmp_lg_u32 s70, 1
	v_add3_u32 v105, v106, v24, s4
	v_or_b32_e32 v24, s6, v88
	s_cselect_b64 s[6:7], -1, 0
	s_bitcmp1_b32 s12, 6
	s_cselect_b64 s[8:9], -1, 0
	s_or_b64 s[64:65], s[6:7], s[8:9]
	s_lshl_b32 s6, s70, 4
	v_lshlrev_b32_e32 v102, 2, v24
	v_or_b32_e32 v24, s6, v84
	v_mul_lo_u32 v24, v24, s83
	v_lshlrev_b32_e32 v68, 2, v23
	v_add_u32_e32 v101, 0, v24
	v_or_b32_e32 v98, s6, v68
	s_and_b32 s6, s12, 0xffffff80
	v_lshrrev_b32_e32 v24, 2, v84
	s_add_i32 s86, s35, s6
	v_or_b32_e32 v24, v26, v24
	s_ashr_i32 s6, s12, 3
	s_lshl_b32 s16, s58, 9
	v_mad_u32_u24 v28, v24, s83, 0
	v_lshlrev_b32_e32 v24, 3, v83
	s_and_b32 s56, s6, -16
	s_add_i32 s42, s42, s16
	v_and_or_b32 v29, v24, 24, s13
	v_or_b32_e32 v24, s56, v84
	s_and_b32 s16, s42, 0xfffff800
	v_mul_lo_u32 v26, v24, s82
	s_or_b32 s17, s16, s17
	v_add_u32_e32 v70, 0, v26
	s_movk_i32 s6, 0x1c0
	v_or_b32_e32 v109, s17, v84
	s_lshl_b32 s17, s70, 6
	v_cmp_gt_u32_e64 s[4:5], 16, v27
	v_lshl_or_b32 v96, s71, 4, v84
	v_mad_u64_u32 v[26:27], s[6:7], v24, s6, v[70:71]
	v_or_b32_e32 v24, 2, v98
	s_add_i32 s17, s17, 0x18500
	v_cmp_gt_i32_e64 s[10:11], v24, v96
	v_or_b32_e32 v24, 3, v98
	v_lshl_or_b32 v111, v23, 4, s17
	v_mul_hi_u32_u24_e32 v23, 0x7000, v84
	s_mul_hi_i32 s42, s16, 0x3800
	v_mul_lo_u32 v108, v25, s87
	v_cmp_gt_i32_e64 s[6:7], v24, v96
	v_mul_u32_u24_e32 v24, 0x7000, v84
	s_mul_i32 s58, s16, 0x3800
	v_or_b32_e32 v25, s42, v23
	s_lshl_b32 s42, s92, 4
	v_or_b32_e32 v23, s58, v24
	s_and_b32 s42, s42, 0x600
	v_or_b32_e32 v23, s42, v23
	s_ashr_i32 s17, s16, 31
	v_lshl_or_b32 v24, s59, 7, v23
	v_mul_lo_u32 v27, v16, s83
	v_lshl_add_u64 v[18:19], v[18:19], 1, v[24:25]
	v_lshl_add_u64 v[16:17], v[16:17], 0, s[16:17]
	s_waitcnt lgkmcnt(0)
	s_barrier
	v_mad_u32_u24 v104, v88, s83, 0
	v_lshl_add_u64 v[72:73], s[28:29], 0, v[18:19]
	v_mad_u64_u32 v[18:19], s[16:17], v16, s84, 0
	v_mul_u32_u24_e32 v20, 0x210, v84
	v_lshlrev_b32_e32 v107, 3, v84
	v_mad_u32_u24 v100, v96, s83, 0
	v_add_u32_e32 v30, 0, v99
	v_mad_i32_i24 v31, v88, s33, v104
	v_mul_u32_u24_e32 v32, 0x50, v84
	v_mad_i32_i24 v17, v17, s84, v19
	v_or3_b32 v16, v18, s42, v60
	v_mov_b32_e32 v36, 0
	v_cmp_gt_i32_e64 s[14:15], 16, v83
	v_mad_i32_i24 v93, v96, s33, v100
	v_lshlrev_b32_e32 v94, 1, v98
	v_lshlrev_b32_e32 v92, 2, v96
	v_lshl_add_u32 v89, v88, 2, s35
	s_ashr_i32 s57, s56, 31
	v_cmp_gt_i32_e64 s[12:13], v98, v96
	v_cmp_lt_i32_e64 s[8:9], v98, v96
	v_lshl_or_b32 v110, s71, 6, v66
	v_lshl_add_u64 v[74:75], s[28:29], 0, v[16:17]
	s_mov_b32 s16, 0
	s_mov_b64 s[70:71], 0
	s_lshl_b32 s58, s97, 1
	v_lshlrev_b32_e32 v60, 1, v68
	v_add_u32_e32 v112, v224, v27
	v_add_u32_e32 v97, v28, v225
	v_add_u32_e32 v95, v30, v32
	v_add_u32_e32 v91, v31, v99
	v_add_u32_e32 v90, v26, v222
	v_add_u32_e32 v113, v22, v20
	v_add_u32_e32 v113, v113, v223
	v_add_u32_e32 v86, v86, v223
	v_add_u32_e32 v85, v85, v223
	v_add_u32_e32 v67, v67, v223
	v_mov_b32_e32 v114, v107
	v_mov_b32_e32 v37, v36
	v_mov_b32_e32 v38, v36
	v_mov_b32_e32 v39, v36
	v_mov_b32_e32 v52, v36
	v_mov_b32_e32 v53, v36
	v_mov_b32_e32 v54, v36
	v_mov_b32_e32 v55, v36
	v_mov_b32_e32 v48, v36
	v_mov_b32_e32 v49, v36
	v_mov_b32_e32 v50, v36
	v_mov_b32_e32 v51, v36
	v_mov_b32_e32 v44, v36
	v_mov_b32_e32 v45, v36
	v_mov_b32_e32 v46, v36
	v_mov_b32_e32 v47, v36
	v_mov_b32_e32 v40, v36
	v_mov_b32_e32 v41, v36
	v_mov_b32_e32 v42, v36
	v_mov_b32_e32 v43, v36
	v_mov_b32_e32 v32, v36
	v_mov_b32_e32 v33, v36
	v_mov_b32_e32 v34, v36
	v_mov_b32_e32 v35, v36
	v_mov_b32_e32 v28, v36
	v_mov_b32_e32 v29, v36
	v_mov_b32_e32 v30, v36
	v_mov_b32_e32 v31, v36
	v_mov_b32_e32 v24, v36
	v_mov_b32_e32 v25, v36
	v_mov_b32_e32 v26, v36
	v_mov_b32_e32 v27, v36
	v_mov_b32_e32 v20, v36
	v_mov_b32_e32 v21, v36
	v_mov_b32_e32 v22, v36
	v_mov_b32_e32 v23, v36
	v_mov_b32_e32 v16, v36
	v_mov_b32_e32 v17, v36
	v_mov_b32_e32 v18, v36
	v_mov_b32_e32 v19, v36
	s_cmp_gt_i32 s55, 3
	s_cbranch_scc1 .Lml_prio_skip
	s_setprio 1
.Lml_prio_skip:
	s_branch .LBB0_662
.LBB0_660:
	s_or_b64 exec, exec, s[72:73]
